# v28 plus attention row-max computed as a depth-4 tree instead of a 17-deep chain
# baseline (speedup 1.0000x reference)
.LBB0_191:
	s_nop 10
	v_max3_f32 v226, v64, v65, v66
	v_max3_f32 v227, v67, v68, v69
	v_max3_f32 v228, v70, v71, v72
	v_max3_f32 v229, v73, v74, v75
	v_max3_f32 v230, v76, v77, v78
	v_max3_f32 v231, v86, v87, v88
	v_max3_f32 v232, v89, v90, v91
	v_max3_f32 v233, v92, v93, v94
	v_max3_f32 v234, v95, v96, v97
	v_max3_f32 v235, v98, v99, v100
	v_max3_f32 v226, v226, v227, v228
	v_max3_f32 v229, v229, v230, v231
	v_max3_f32 v232, v232, v233, v234
	v_max3_f32 v235, v235, v79, v101
	v_max3_f32 v226, v226, v229, v232
	v_max_f32_e32 v84, v226, v235
	ds_bpermute_b32 v155, v133, v84
	s_waitcnt lgkmcnt(0)
	v_max_f32_e32 v155, v155, v155
	v_max_f32_e32 v84, v84, v155
	v_cmp_lt_f32_e32 vcc, s82, v84
	s_cbranch_vccz .LBB0_193
	v_max_f32_e32 v84, v84, v84
	v_max_f32_e32 v84, 0, v84
	v_exp_f32_e64 v204, -v84
	v_add_f32_e32 v202, v202, v84
	v_pk_add_f32 v[86:87], v[86:87], v[84:85] op_sel_hi:[1,0] neg_lo:[0,1] neg_hi:[0,1]
	v_pk_add_f32 v[64:65], v[64:65], v[84:85] op_sel_hi:[1,0] neg_lo:[0,1] neg_hi:[0,1]
	v_pk_add_f32 v[88:89], v[88:89], v[84:85] op_sel_hi:[1,0] neg_lo:[0,1] neg_hi:[0,1]
	v_pk_add_f32 v[66:67], v[66:67], v[84:85] op_sel_hi:[1,0] neg_lo:[0,1] neg_hi:[0,1]
	v_pk_add_f32 v[90:91], v[90:91], v[84:85] op_sel_hi:[1,0] neg_lo:[0,1] neg_hi:[0,1]
	v_pk_add_f32 v[68:69], v[68:69], v[84:85] op_sel_hi:[1,0] neg_lo:[0,1] neg_hi:[0,1]
	v_pk_add_f32 v[92:93], v[92:93], v[84:85] op_sel_hi:[1,0] neg_lo:[0,1] neg_hi:[0,1]
	v_pk_add_f32 v[70:71], v[70:71], v[84:85] op_sel_hi:[1,0] neg_lo:[0,1] neg_hi:[0,1]
	v_pk_add_f32 v[94:95], v[94:95], v[84:85] op_sel_hi:[1,0] neg_lo:[0,1] neg_hi:[0,1]
	v_pk_add_f32 v[72:73], v[72:73], v[84:85] op_sel_hi:[1,0] neg_lo:[0,1] neg_hi:[0,1]
	v_pk_add_f32 v[96:97], v[96:97], v[84:85] op_sel_hi:[1,0] neg_lo:[0,1] neg_hi:[0,1]
	v_pk_add_f32 v[74:75], v[74:75], v[84:85] op_sel_hi:[1,0] neg_lo:[0,1] neg_hi:[0,1]
	v_pk_add_f32 v[98:99], v[98:99], v[84:85] op_sel_hi:[1,0] neg_lo:[0,1] neg_hi:[0,1]
	v_pk_add_f32 v[76:77], v[76:77], v[84:85] op_sel_hi:[1,0] neg_lo:[0,1] neg_hi:[0,1]
	v_pk_add_f32 v[100:101], v[100:101], v[84:85] op_sel_hi:[1,0] neg_lo:[0,1] neg_hi:[0,1]
	v_pk_add_f32 v[78:79], v[78:79], v[84:85] op_sel_hi:[1,0] neg_lo:[0,1] neg_hi:[0,1]
	v_pk_mul_f32 v[62:63], v[62:63], v[204:205] op_sel_hi:[1,0]
	v_pk_mul_f32 v[60:61], v[60:61], v[204:205] op_sel_hi:[1,0]
	v_pk_mul_f32 v[58:59], v[58:59], v[204:205] op_sel_hi:[1,0]
	v_pk_mul_f32 v[56:57], v[56:57], v[204:205] op_sel_hi:[1,0]
	v_pk_mul_f32 v[54:55], v[54:55], v[204:205] op_sel_hi:[1,0]
	v_pk_mul_f32 v[52:53], v[52:53], v[204:205] op_sel_hi:[1,0]
	v_pk_mul_f32 v[50:51], v[50:51], v[204:205] op_sel_hi:[1,0]
	v_pk_mul_f32 v[48:49], v[48:49], v[204:205] op_sel_hi:[1,0]
	v_pk_mul_f32 v[46:47], v[46:47], v[204:205] op_sel_hi:[1,0]
	v_pk_mul_f32 v[44:45], v[44:45], v[204:205] op_sel_hi:[1,0]
	v_pk_mul_f32 v[42:43], v[42:43], v[204:205] op_sel_hi:[1,0]
	v_pk_mul_f32 v[40:41], v[40:41], v[204:205] op_sel_hi:[1,0]
	v_pk_mul_f32 v[38:39], v[38:39], v[204:205] op_sel_hi:[1,0]
	v_pk_mul_f32 v[36:37], v[36:37], v[204:205] op_sel_hi:[1,0]
	v_pk_mul_f32 v[34:35], v[34:35], v[204:205] op_sel_hi:[1,0]
	v_pk_mul_f32 v[32:33], v[32:33], v[204:205] op_sel_hi:[1,0]
	v_pk_mul_f32 v[30:31], v[30:31], v[204:205] op_sel_hi:[1,0]
	v_pk_mul_f32 v[28:29], v[28:29], v[204:205] op_sel_hi:[1,0]
	v_pk_mul_f32 v[26:27], v[26:27], v[204:205] op_sel_hi:[1,0]
	v_pk_mul_f32 v[24:25], v[24:25], v[204:205] op_sel_hi:[1,0]
	v_pk_mul_f32 v[22:23], v[22:23], v[204:205] op_sel_hi:[1,0]
	v_pk_mul_f32 v[20:21], v[20:21], v[204:205] op_sel_hi:[1,0]
	v_pk_mul_f32 v[18:19], v[18:19], v[204:205] op_sel_hi:[1,0]
	v_pk_mul_f32 v[16:17], v[16:17], v[204:205] op_sel_hi:[1,0]
	v_pk_mul_f32 v[14:15], v[14:15], v[204:205] op_sel_hi:[1,0]
	v_pk_mul_f32 v[12:13], v[12:13], v[204:205] op_sel_hi:[1,0]
	v_pk_mul_f32 v[10:11], v[10:11], v[204:205] op_sel_hi:[1,0]
	v_pk_mul_f32 v[8:9], v[8:9], v[204:205] op_sel_hi:[1,0]
	v_pk_mul_f32 v[6:7], v[6:7], v[204:205] op_sel_hi:[1,0]
	v_pk_mul_f32 v[4:5], v[4:5], v[204:205] op_sel_hi:[1,0]
	v_pk_mul_f32 v[2:3], v[2:3], v[204:205] op_sel_hi:[1,0]
	v_pk_mul_f32 v[0:1], v[0:1], v[204:205] op_sel_hi:[1,0]
	v_mul_f32_e32 v203, v203, v204

.LBB0_208:
	s_nop 10
	v_max3_f32 v226, v64, v65, v66
	v_max3_f32 v227, v67, v68, v69
	v_max3_f32 v228, v70, v71, v72
	v_max3_f32 v229, v73, v74, v75
	v_max3_f32 v230, v76, v77, v78
	v_max3_f32 v231, v86, v87, v88
	v_max3_f32 v232, v89, v90, v91
	v_max3_f32 v233, v92, v93, v94
	v_max3_f32 v234, v95, v96, v97
	v_max3_f32 v235, v98, v99, v100
	v_max3_f32 v226, v226, v227, v228
	v_max3_f32 v229, v229, v230, v231
	v_max3_f32 v232, v232, v233, v234
	v_max3_f32 v235, v235, v79, v101
	v_max3_f32 v226, v226, v229, v232
	v_max_f32_e32 v84, v226, v235
	ds_bpermute_b32 v155, v133, v84
	s_waitcnt lgkmcnt(0)
	v_max_f32_e32 v155, v155, v155
	v_max_f32_e32 v84, v84, v155
	v_cmp_lt_f32_e32 vcc, s82, v84
	s_cbranch_vccz .LBB0_210
	v_max_f32_e32 v84, v84, v84
	v_max_f32_e32 v84, 0, v84
	v_exp_f32_e64 v166, -v84
	v_add_f32_e32 v164, v164, v84
	v_pk_add_f32 v[86:87], v[86:87], v[84:85] op_sel_hi:[1,0] neg_lo:[0,1] neg_hi:[0,1]
	v_pk_add_f32 v[64:65], v[64:65], v[84:85] op_sel_hi:[1,0] neg_lo:[0,1] neg_hi:[0,1]
	v_pk_add_f32 v[88:89], v[88:89], v[84:85] op_sel_hi:[1,0] neg_lo:[0,1] neg_hi:[0,1]
	v_pk_add_f32 v[66:67], v[66:67], v[84:85] op_sel_hi:[1,0] neg_lo:[0,1] neg_hi:[0,1]
	v_pk_add_f32 v[90:91], v[90:91], v[84:85] op_sel_hi:[1,0] neg_lo:[0,1] neg_hi:[0,1]
	v_pk_add_f32 v[68:69], v[68:69], v[84:85] op_sel_hi:[1,0] neg_lo:[0,1] neg_hi:[0,1]
	v_pk_add_f32 v[92:93], v[92:93], v[84:85] op_sel_hi:[1,0] neg_lo:[0,1] neg_hi:[0,1]
	v_pk_add_f32 v[70:71], v[70:71], v[84:85] op_sel_hi:[1,0] neg_lo:[0,1] neg_hi:[0,1]
	v_pk_add_f32 v[94:95], v[94:95], v[84:85] op_sel_hi:[1,0] neg_lo:[0,1] neg_hi:[0,1]
	v_pk_add_f32 v[72:73], v[72:73], v[84:85] op_sel_hi:[1,0] neg_lo:[0,1] neg_hi:[0,1]
	v_pk_add_f32 v[96:97], v[96:97], v[84:85] op_sel_hi:[1,0] neg_lo:[0,1] neg_hi:[0,1]
	v_pk_add_f32 v[74:75], v[74:75], v[84:85] op_sel_hi:[1,0] neg_lo:[0,1] neg_hi:[0,1]
	v_pk_add_f32 v[98:99], v[98:99], v[84:85] op_sel_hi:[1,0] neg_lo:[0,1] neg_hi:[0,1]
	v_pk_add_f32 v[76:77], v[76:77], v[84:85] op_sel_hi:[1,0] neg_lo:[0,1] neg_hi:[0,1]
	v_pk_add_f32 v[100:101], v[100:101], v[84:85] op_sel_hi:[1,0] neg_lo:[0,1] neg_hi:[0,1]
	v_pk_add_f32 v[78:79], v[78:79], v[84:85] op_sel_hi:[1,0] neg_lo:[0,1] neg_hi:[0,1]
	v_pk_mul_f32 v[62:63], v[62:63], v[166:167] op_sel_hi:[1,0]
	v_pk_mul_f32 v[60:61], v[60:61], v[166:167] op_sel_hi:[1,0]
	v_pk_mul_f32 v[58:59], v[58:59], v[166:167] op_sel_hi:[1,0]
	v_pk_mul_f32 v[56:57], v[56:57], v[166:167] op_sel_hi:[1,0]
	v_pk_mul_f32 v[54:55], v[54:55], v[166:167] op_sel_hi:[1,0]
	v_pk_mul_f32 v[52:53], v[52:53], v[166:167] op_sel_hi:[1,0]
	v_pk_mul_f32 v[50:51], v[50:51], v[166:167] op_sel_hi:[1,0]
	v_pk_mul_f32 v[48:49], v[48:49], v[166:167] op_sel_hi:[1,0]
	v_pk_mul_f32 v[46:47], v[46:47], v[166:167] op_sel_hi:[1,0]
	v_pk_mul_f32 v[44:45], v[44:45], v[166:167] op_sel_hi:[1,0]
	v_pk_mul_f32 v[42:43], v[42:43], v[166:167] op_sel_hi:[1,0]
	v_pk_mul_f32 v[40:41], v[40:41], v[166:167] op_sel_hi:[1,0]
	v_pk_mul_f32 v[38:39], v[38:39], v[166:167] op_sel_hi:[1,0]
	v_pk_mul_f32 v[36:37], v[36:37], v[166:167] op_sel_hi:[1,0]
	v_pk_mul_f32 v[34:35], v[34:35], v[166:167] op_sel_hi:[1,0]
	v_pk_mul_f32 v[32:33], v[32:33], v[166:167] op_sel_hi:[1,0]
	v_pk_mul_f32 v[30:31], v[30:31], v[166:167] op_sel_hi:[1,0]
	v_pk_mul_f32 v[28:29], v[28:29], v[166:167] op_sel_hi:[1,0]
	v_pk_mul_f32 v[26:27], v[26:27], v[166:167] op_sel_hi:[1,0]
	v_pk_mul_f32 v[24:25], v[24:25], v[166:167] op_sel_hi:[1,0]
	v_pk_mul_f32 v[22:23], v[22:23], v[166:167] op_sel_hi:[1,0]
	v_pk_mul_f32 v[20:21], v[20:21], v[166:167] op_sel_hi:[1,0]
	v_pk_mul_f32 v[18:19], v[18:19], v[166:167] op_sel_hi:[1,0]
	v_pk_mul_f32 v[16:17], v[16:17], v[166:167] op_sel_hi:[1,0]
	v_pk_mul_f32 v[14:15], v[14:15], v[166:167] op_sel_hi:[1,0]
	v_pk_mul_f32 v[12:13], v[12:13], v[166:167] op_sel_hi:[1,0]
	v_pk_mul_f32 v[10:11], v[10:11], v[166:167] op_sel_hi:[1,0]
	v_pk_mul_f32 v[8:9], v[8:9], v[166:167] op_sel_hi:[1,0]
	v_pk_mul_f32 v[6:7], v[6:7], v[166:167] op_sel_hi:[1,0]
	v_pk_mul_f32 v[4:5], v[4:5], v[166:167] op_sel_hi:[1,0]
	v_pk_mul_f32 v[2:3], v[2:3], v[166:167] op_sel_hi:[1,0]
	v_pk_mul_f32 v[0:1], v[0:1], v[166:167] op_sel_hi:[1,0]
	v_mul_f32_e32 v165, v165, v166
